# dnpre: batched l2norm reduction (16 tokens per array reduced together via permlane swaps + DPP, one rsq per register)
# speedup vs baseline: 1.2037x; 1.0019x over previous
; __device__ __forceinline__ float bf2f(u16 h) { return __uint_as_float(((unsigned)h) << 16); }
; __device__ __forceinline__ float wave_sum(float v) {
;   v += dpp_f<DPP_XOR1>(v);
;   v += dpp_f<DPP_XOR2>(v);
;   v += dpp_f<DPP_HMIRROR>(v);
;   v += dpp_f<DPP_MIRROR>(v);
;   float a = __int_as_float(__builtin_amdgcn_readlane(__float_as_int(v), 0));
;   float b = __int_as_float(__builtin_amdgcn_readlane(__float_as_int(v), 16));
;   float c = __int_as_float(__builtin_amdgcn_readlane(__float_as_int(v), 32));
;   float d = __int_as_float(__builtin_amdgcn_readlane(__float_as_int(v), 48));
;   return (a + b) + (c + d);
; }
; __device__ __forceinline__ float silu(float y) { return y / (1.f + __expf(-y)); }
; __device__ void ph_dnpre(const P& p, float* lds) {
;     ...
;       for (int arr = 0; arr < 3; ++arr) {
;         const int ch = arr * 512 + h * 64 + lane;
;         const float w0 = p.conv_w[ch], w1 = p.conv_w[1536 + ch], w2 = p.conv_w[3072 + ch], w3 = p.conv_w[4608 + ch];
;         float* dst = arr == 0 ? B0 : (arr == 1 ? B1 : B2);
; #pragma unroll
;         for (int i = 0; i < 16; ++i) {
;           float y = silu(w0 * bf2f(xr[arr][i]) + w1 * bf2f(xr[arr][i + 1]) + w2 * bf2f(xr[arr][i + 2]) + w3 * bf2f(xr[arr][i + 3]));
;           if (arr < 2) {
;             float ss = wave_sum(y * y);
;             y *= rsqrtf(ss + EPS) * (arr == 0 ? 0.125f : 1.f);
;           }
;           dst[(w * 16 + i) * LS + lane] = y;
;         }
;       }
.LBB0_176:
	s_bfe_u32 s3, s2, 0x30007
	v_readlane_b32 s80, v228, 33
	v_lshl_or_b32 v44, s3, 8, v60
	v_readlane_b32 s84, v228, 37
	v_readlane_b32 s85, v228, 38
	v_and_b32_e32 v179, 0xffff0000, v175
	v_lshlrev_b32_e32 v178, 16, v175
	v_lshl_add_u64 v[4:5], s[84:85], 0, v[44:45]
	v_add_co_u32_e32 v0, vcc, 0x1000, v4
	s_nop 0
	global_load_dword v6, v44, s[84:85]
	v_addc_co_u32_e32 v1, vcc, 0, v5, vcc
	v_add_co_u32_e32 v8, vcc, 0x3000, v4
	global_load_dword v7, v[0:1], off offset:2048
	s_nop 0
	v_addc_co_u32_e32 v9, vcc, 0, v5, vcc
	v_add_co_u32_e32 v2, vcc, 0x4000, v4
	global_load_dword v10, v[8:9], off
	s_nop 0
	v_addc_co_u32_e32 v3, vcc, 0, v5, vcc
	global_load_dword v11, v[2:3], off offset:2048
	v_lshlrev_b32_e32 v182, 16, v176
	v_and_b32_e32 v183, 0xffff0000, v176
	v_lshlrev_b32_e32 v161, 16, v161
	v_lshlrev_b32_e32 v59, 16, v59
	v_lshlrev_b32_e32 v151, 16, v151
	v_readlane_b32 s81, v228, 34
	v_readlane_b32 s82, v228, 35
	v_readlane_b32 s83, v228, 36
	v_readlane_b32 s86, v228, 39
	v_readlane_b32 s87, v228, 40
	v_readlane_b32 s88, v228, 41
	v_readlane_b32 s89, v228, 42
	v_readlane_b32 s90, v228, 43
	v_readlane_b32 s91, v228, 44
	v_readlane_b32 s92, v228, 45
	v_readlane_b32 s93, v228, 46
	v_readlane_b32 s94, v228, 47
	v_readlane_b32 s95, v228, 48
	s_waitcnt vmcnt(2)
	v_pk_mul_f32 v[180:181], v[6:7], v[178:179]
	s_nop 0
	v_add_f32_e32 v175, v180, v181
	s_waitcnt vmcnt(0)
	v_pk_mul_f32 v[176:177], v[10:11], v[182:183]
	s_nop 0
	v_add_f32_e32 v175, v175, v176
	v_add_f32_e32 v175, v175, v177
	v_mul_f32_e32 v176, 0xbfb8aa3b, v175
	v_exp_f32_e32 v176, v176
	s_nop 0
	v_add_f32_e32 v176, 1.0, v176
	v_div_scale_f32 v177, s[10:11], v176, v176, v175
	v_rcp_f32_e32 v180, v177
	s_nop 0
	v_fma_f32 v181, -v177, v180, 1.0
	v_fmac_f32_e32 v180, v181, v180
	v_div_scale_f32 v181, vcc, v175, v176, v175
	v_mul_f32_e32 v184, v181, v180
	v_fma_f32 v185, -v177, v184, v181
	v_fmac_f32_e32 v184, v185, v180
	v_fma_f32 v177, -v177, v184, v181
	v_div_fmas_f32 v177, v177, v180, v184
	v_div_fixup_f32 v186, v177, v176, v175
	v_pk_mov_b32 v[176:177], v[178:179], v[182:183] op_sel:[1,0]
	v_lshlrev_b32_e32 v175, 16, v174
	s_nop 1
	v_pk_mul_f32 v[176:177], v[6:7], v[176:177]
	v_mov_b32_e32 v174, v183
	v_pk_mul_f32 v[178:179], v[10:11], v[174:175]
	v_add_f32_e32 v176, v176, v177
	v_add_f32_e32 v176, v176, v178
	v_add_f32_e32 v176, v176, v179
	v_mul_f32_e32 v177, 0xbfb8aa3b, v176
	v_exp_f32_e32 v177, v177
	s_nop 0
	v_add_f32_e32 v177, 1.0, v177
	v_div_scale_f32 v178, s[10:11], v177, v177, v176
	v_rcp_f32_e32 v179, v178
	s_nop 0
	v_fma_f32 v181, -v178, v179, 1.0
	v_fmac_f32_e32 v179, v181, v179
	v_div_scale_f32 v181, vcc, v176, v177, v176
	v_mul_f32_e32 v184, v181, v179
	v_fma_f32 v185, -v178, v184, v181
	v_fmac_f32_e32 v184, v185, v179
	v_fma_f32 v178, -v178, v184, v181
	v_div_fmas_f32 v178, v178, v179, v184
	v_div_fixup_f32 v187, v178, v177, v176
	v_mov_b32_e32 v179, v175
	s_nop 0
	v_mov_b32_e32 v226, v69
	v_mov_b32_e32 v176, v6
	v_mov_b32_e32 v177, v10
	v_mov_b32_e32 v178, v182
	v_pk_mul_f32 v[176:177], v[176:177], v[178:179]
	v_lshlrev_b32_e32 v180, 16, v173
	v_fma_f32 v173, v7, v183, v176
	v_add_f32_e32 v173, v173, v177
	v_fmac_f32_e32 v173, v11, v180
	v_mul_f32_e32 v176, 0xbfb8aa3b, v173
	v_exp_f32_e32 v176, v176
	s_nop 0
	v_add_f32_e32 v176, 1.0, v176
	v_div_scale_f32 v177, s[10:11], v176, v176, v173
	v_rcp_f32_e32 v178, v177
	s_nop 0
	v_fma_f32 v179, -v177, v178, 1.0
	v_fmac_f32_e32 v178, v179, v178
	v_div_scale_f32 v179, vcc, v173, v176, v173
	v_mul_f32_e32 v181, v179, v178
	v_fma_f32 v182, -v177, v181, v179
	v_fmac_f32_e32 v181, v182, v178
	v_fma_f32 v177, -v177, v181, v179
	v_div_fmas_f32 v177, v177, v178, v181
	v_div_fixup_f32 v188, v177, v176, v173
	v_lshlrev_b32_e32 v177, 16, v172
	v_pk_mul_f32 v[172:173], v[6:7], v[174:175]
	s_nop 0
	s_nop 1
	v_add_f32_e32 v172, v172, v173
	v_fmac_f32_e32 v172, v10, v180
	v_fmac_f32_e32 v172, v11, v177
	v_mul_f32_e32 v173, 0xbfb8aa3b, v172
	v_exp_f32_e32 v173, v173
	s_nop 0
	v_add_f32_e32 v173, 1.0, v173
	v_div_scale_f32 v174, s[10:11], v173, v173, v172
	v_rcp_f32_e32 v178, v174
	s_nop 0
	v_fma_f32 v179, -v174, v178, 1.0
	v_fmac_f32_e32 v178, v179, v178
	v_div_scale_f32 v179, vcc, v172, v173, v172
	v_mul_f32_e32 v181, v179, v178
	v_fma_f32 v182, -v174, v181, v179
	v_fmac_f32_e32 v181, v182, v178
	v_fma_f32 v174, -v174, v181, v179
	v_div_fmas_f32 v174, v174, v178, v181
	v_div_fixup_f32 v189, v174, v173, v172
	v_lshlrev_b32_e32 v174, 16, v171
	v_mul_f32_e32 v171, v7, v180
	v_fmac_f32_e32 v171, v6, v175
	v_fmac_f32_e32 v171, v10, v177
	s_nop 0
	v_fmac_f32_e32 v171, v11, v174
	s_nop 0
	v_mul_f32_e32 v172, 0xbfb8aa3b, v171
	v_exp_f32_e32 v172, v172
	s_nop 0
	v_add_f32_e32 v172, 1.0, v172
	v_div_scale_f32 v173, s[10:11], v172, v172, v171
	v_rcp_f32_e32 v175, v173
	s_nop 0
	v_fma_f32 v176, -v173, v175, 1.0
	v_fmac_f32_e32 v175, v176, v175
	v_div_scale_f32 v176, vcc, v171, v172, v171
	v_mul_f32_e32 v178, v176, v175
	v_fma_f32 v179, -v173, v178, v176
	v_fmac_f32_e32 v178, v179, v175
	v_fma_f32 v173, -v173, v178, v176
	v_div_fmas_f32 v173, v173, v175, v178
	v_div_fixup_f32 v190, v173, v172, v171
	v_lshlrev_b32_e32 v173, 16, v170
	v_mul_f32_e32 v170, v7, v177
	v_fmac_f32_e32 v170, v6, v180
	v_fmac_f32_e32 v170, v10, v174
	s_nop 0
	v_fmac_f32_e32 v170, v11, v173
	s_nop 0
	v_mul_f32_e32 v171, 0xbfb8aa3b, v170
	v_exp_f32_e32 v171, v171
	s_nop 0
	v_add_f32_e32 v171, 1.0, v171
	v_div_scale_f32 v175, s[10:11], v171, v171, v170
	v_rcp_f32_e32 v176, v175
	s_nop 0
	v_fma_f32 v178, -v175, v176, 1.0
	v_fmac_f32_e32 v176, v178, v176
	v_div_scale_f32 v178, vcc, v170, v171, v170
	v_mul_f32_e32 v179, v178, v176
	v_fma_f32 v180, -v175, v179, v178
; __device__ __forceinline__ float bf2f(u16 h) { return __uint_as_float(((unsigned)h) << 16); }
; __device__ __forceinline__ float silu(float y) { return y / (1.f + __expf(-y)); }
; __device__ void ph_dnpre(const P& p, float* lds) {
;     ...
; #pragma unroll
;         for (int i = 0; i < 16; ++i) {
;           float y = silu(w0 * bf2f(xr[arr][i]) + w1 * bf2f(xr[arr][i + 1]) + w2 * bf2f(xr[arr][i + 2]) + w3 * bf2f(xr[arr][i + 3]));
;           if (arr < 2) {
;             float ss = wave_sum(y * y);
;             y *= rsqrtf(ss + EPS) * (arr == 0 ? 0.125f : 1.f);
;           }
;           dst[(w * 16 + i) * LS + lane] = y;
;         }
;       }
	v_fmac_f32_e32 v179, v180, v176
	v_fma_f32 v175, -v175, v179, v178
	v_div_fmas_f32 v175, v175, v176, v179
	v_div_fixup_f32 v191, v175, v171, v170
	v_add_u32_e32 v175, 0x400, v69
	v_lshlrev_b32_e32 v172, 16, v169
	v_mul_f32_e32 v169, v7, v174
	v_fmac_f32_e32 v169, v6, v177
	v_fmac_f32_e32 v169, v10, v173
	v_fmac_f32_e32 v169, v11, v172
	v_mul_f32_e32 v170, 0xbfb8aa3b, v169
	v_exp_f32_e32 v170, v170
	s_nop 0
	v_add_f32_e32 v170, 1.0, v170
	v_div_scale_f32 v171, s[10:11], v170, v170, v169
	v_rcp_f32_e32 v176, v171
	s_nop 0
	v_fma_f32 v177, -v171, v176, 1.0
	v_fmac_f32_e32 v176, v177, v176
	v_div_scale_f32 v177, vcc, v169, v170, v169
	v_mul_f32_e32 v178, v177, v176
	v_fma_f32 v179, -v171, v178, v177
	v_fmac_f32_e32 v178, v179, v176
	v_fma_f32 v171, -v171, v178, v177
	v_div_fmas_f32 v171, v171, v176, v178
	v_div_fixup_f32 v192, v171, v170, v169
	v_lshlrev_b32_e32 v176, 16, v167
	v_mul_f32_e32 v167, v7, v173
	s_nop 1
	v_fmac_f32_e32 v167, v6, v174
	v_fmac_f32_e32 v167, v10, v172
	s_nop 0
	v_fmac_f32_e32 v167, v11, v176
	s_nop 0
	s_nop 3
	v_mul_f32_e32 v170, 0xbfb8aa3b, v167
	v_exp_f32_e32 v170, v170
	s_nop 0
	v_add_f32_e32 v170, 1.0, v170
	v_div_scale_f32 v171, s[10:11], v170, v170, v167
	v_rcp_f32_e32 v174, v171
	s_nop 0
	v_fma_f32 v177, -v171, v174, 1.0
	v_fmac_f32_e32 v174, v177, v174
	v_div_scale_f32 v177, vcc, v167, v170, v167
	v_mul_f32_e32 v178, v177, v174
	v_fma_f32 v179, -v171, v178, v177
	v_fmac_f32_e32 v178, v179, v174
	v_fma_f32 v171, -v171, v178, v177
	v_div_fmas_f32 v171, v171, v174, v178
	v_div_fixup_f32 v193, v171, v170, v167
	v_mul_f32_e32 v167, v7, v172
	s_nop 3
	v_fmac_f32_e32 v167, v6, v173
	v_lshlrev_b32_e32 v170, 16, v168
	v_fmac_f32_e32 v167, v10, v176
	v_fmac_f32_e32 v167, v11, v170
	v_mul_f32_e32 v168, 0xbfb8aa3b, v167
	v_exp_f32_e32 v168, v168
	s_nop 0
	v_add_f32_e32 v168, 1.0, v168
	v_div_scale_f32 v169, s[10:11], v168, v168, v167
	v_rcp_f32_e32 v171, v169
	s_nop 0
	v_fma_f32 v173, -v169, v171, 1.0
	v_fmac_f32_e32 v171, v173, v171
	v_div_scale_f32 v173, vcc, v167, v168, v167
	v_mul_f32_e32 v174, v173, v171
	v_fma_f32 v175, -v169, v174, v173
	v_fmac_f32_e32 v174, v175, v171
	v_fma_f32 v169, -v169, v174, v173
	v_div_fmas_f32 v169, v169, v171, v174
	v_div_fixup_f32 v194, v169, v168, v167
	v_lshlrev_b32_e32 v169, 16, v166
	v_mul_f32_e32 v166, v7, v176
	v_fmac_f32_e32 v166, v6, v172
	v_fmac_f32_e32 v166, v10, v170
	s_nop 0
	v_fmac_f32_e32 v166, v11, v169
	s_nop 0
	v_mul_f32_e32 v167, 0xbfb8aa3b, v166
	v_exp_f32_e32 v167, v167
	s_nop 0
	v_add_f32_e32 v167, 1.0, v167
	v_div_scale_f32 v171, s[10:11], v167, v167, v166
	v_rcp_f32_e32 v172, v171
	s_nop 0
	v_fma_f32 v173, -v171, v172, 1.0
	v_fmac_f32_e32 v172, v173, v172
	v_div_scale_f32 v173, vcc, v166, v167, v166
	v_mul_f32_e32 v174, v173, v172
	v_fma_f32 v175, -v171, v174, v173
	v_fmac_f32_e32 v174, v175, v172
	v_fma_f32 v171, -v171, v174, v173
	v_div_fmas_f32 v171, v171, v172, v174
	v_div_fixup_f32 v195, v171, v167, v166
	v_add_u32_e32 v171, 0x800, v69
	v_lshlrev_b32_e32 v168, 16, v165
	v_mul_f32_e32 v165, v7, v170
	v_fmac_f32_e32 v165, v6, v176
	v_fmac_f32_e32 v165, v10, v169
	v_fmac_f32_e32 v165, v11, v168
	v_mul_f32_e32 v166, 0xbfb8aa3b, v165
	v_exp_f32_e32 v166, v166
	s_nop 0
	v_add_f32_e32 v166, 1.0, v166
	v_div_scale_f32 v167, s[10:11], v166, v166, v165
	v_rcp_f32_e32 v172, v167
	s_nop 0
	v_fma_f32 v173, -v167, v172, 1.0
	v_fmac_f32_e32 v172, v173, v172
	v_div_scale_f32 v173, vcc, v165, v166, v165
	v_mul_f32_e32 v174, v173, v172
	v_fma_f32 v175, -v167, v174, v173
	v_fmac_f32_e32 v174, v175, v172
	v_fma_f32 v167, -v167, v174, v173
	v_div_fmas_f32 v167, v167, v172, v174
	v_div_fixup_f32 v196, v167, v166, v165
	v_lshlrev_b32_e32 v167, 16, v164
	v_mul_f32_e32 v164, v7, v169
	v_fmac_f32_e32 v164, v6, v170
	v_fmac_f32_e32 v164, v10, v168
	s_nop 0
	v_fmac_f32_e32 v164, v11, v167
	s_nop 0
	v_mul_f32_e32 v165, 0xbfb8aa3b, v164
	v_exp_f32_e32 v165, v165
	s_nop 0
	v_add_f32_e32 v165, 1.0, v165
	v_div_scale_f32 v170, s[10:11], v165, v165, v164
	v_rcp_f32_e32 v172, v170
	s_nop 0
	v_fma_f32 v173, -v170, v172, 1.0
	v_fmac_f32_e32 v172, v173, v172
	v_div_scale_f32 v173, vcc, v164, v165, v164
	v_mul_f32_e32 v174, v173, v172
	v_fma_f32 v175, -v170, v174, v173
	v_fmac_f32_e32 v174, v175, v172
	v_fma_f32 v170, -v170, v174, v173
	v_div_fmas_f32 v170, v170, v172, v174
	v_div_fixup_f32 v197, v170, v165, v164
	v_lshlrev_b32_e32 v166, 16, v163
	v_mul_f32_e32 v163, v7, v168
	v_fmac_f32_e32 v163, v6, v169
	v_fmac_f32_e32 v163, v10, v167
	v_fmac_f32_e32 v163, v11, v166
	v_mul_f32_e32 v164, 0xbfb8aa3b, v163
	v_exp_f32_e32 v164, v164
	s_nop 0
	v_add_f32_e32 v164, 1.0, v164
	v_div_scale_f32 v165, s[10:11], v164, v164, v163
	v_rcp_f32_e32 v169, v165
	s_nop 0
	v_fma_f32 v170, -v165, v169, 1.0
	v_fmac_f32_e32 v169, v170, v169
	v_div_scale_f32 v170, vcc, v163, v164, v163
	v_mul_f32_e32 v171, v170, v169
	v_fma_f32 v172, -v165, v171, v170
	v_fmac_f32_e32 v171, v172, v169
	v_fma_f32 v165, -v165, v171, v170
	v_div_fmas_f32 v165, v165, v169, v171
	v_div_fixup_f32 v198, v165, v164, v163
	v_lshlrev_b32_e32 v165, 16, v162
	v_mul_f32_e32 v162, v7, v167
	v_fmac_f32_e32 v162, v6, v168
	v_fmac_f32_e32 v162, v10, v166
	s_nop 0
	v_fmac_f32_e32 v162, v11, v165
	s_nop 0
	v_mul_f32_e32 v163, 0xbfb8aa3b, v162
	v_exp_f32_e32 v163, v163
	s_nop 0
	v_add_f32_e32 v163, 1.0, v163
	v_div_scale_f32 v168, s[10:11], v163, v163, v162
	v_rcp_f32_e32 v169, v168
	s_nop 0
	v_fma_f32 v170, -v168, v169, 1.0
	v_fmac_f32_e32 v169, v170, v169
	v_div_scale_f32 v170, vcc, v162, v163, v162
	v_mul_f32_e32 v171, v170, v169
	v_fma_f32 v172, -v168, v171, v170
	v_fmac_f32_e32 v171, v172, v169
	v_fma_f32 v168, -v168, v171, v170
; __device__ __forceinline__ float bf2f(u16 h) { return __uint_as_float(((unsigned)h) << 16); }
; __device__ __forceinline__ float wave_sum(float v) {
;   v += dpp_f<DPP_XOR1>(v);
;   v += dpp_f<DPP_XOR2>(v);
;   v += dpp_f<DPP_HMIRROR>(v);
;   v += dpp_f<DPP_MIRROR>(v);
;   float a = __int_as_float(__builtin_amdgcn_readlane(__float_as_int(v), 0));
;   float b = __int_as_float(__builtin_amdgcn_readlane(__float_as_int(v), 16));
;   float c = __int_as_float(__builtin_amdgcn_readlane(__float_as_int(v), 32));
;   float d = __int_as_float(__builtin_amdgcn_readlane(__float_as_int(v), 48));
;   return (a + b) + (c + d);
; }
; __device__ __forceinline__ float silu(float y) { return y / (1.f + __expf(-y)); }
; __device__ void ph_dnpre(const P& p, float* lds) {
;     ...
; #pragma unroll
;         for (int i = 0; i < 16; ++i) {
;           float y = silu(w0 * bf2f(xr[arr][i]) + w1 * bf2f(xr[arr][i + 1]) + w2 * bf2f(xr[arr][i + 2]) + w3 * bf2f(xr[arr][i + 3]));
;           if (arr < 2) {
;             float ss = wave_sum(y * y);
;             y *= rsqrtf(ss + EPS) * (arr == 0 ? 0.125f : 1.f);
;           }
;           dst[(w * 16 + i) * LS + lane] = y;
;         }
;       }
	v_div_fmas_f32 v168, v168, v169, v171
	v_div_fixup_f32 v199, v168, v163, v162
	v_add_u32_e32 v168, 0xc00, v69
	v_mul_f32_e32 v162, v7, v166
	v_fmac_f32_e32 v162, v6, v167
	v_fmac_f32_e32 v162, v10, v165
	v_fmac_f32_e32 v162, v11, v161
	v_mul_f32_e32 v163, 0xbfb8aa3b, v162
	v_exp_f32_e32 v163, v163
	v_mul_f32_e32 v7, v7, v165
	v_fmac_f32_e32 v7, v6, v166
	v_fmac_f32_e32 v7, v10, v161
	v_add_f32_e32 v163, 1.0, v163
	v_div_scale_f32 v164, s[10:11], v163, v163, v162
	v_rcp_f32_e32 v167, v164
	v_lshlrev_b32_e32 v6, 16, v160
	v_fmac_f32_e32 v7, v11, v6
	v_mul_f32_e32 v6, 0xbfb8aa3b, v7
	v_fma_f32 v169, -v164, v167, 1.0
	v_fmac_f32_e32 v167, v169, v167
	v_div_scale_f32 v169, vcc, v162, v163, v162
	v_mul_f32_e32 v170, v169, v167
	v_fma_f32 v171, -v164, v170, v169
	v_fmac_f32_e32 v170, v171, v167
	v_fma_f32 v164, -v164, v170, v169
	v_div_fmas_f32 v164, v164, v167, v170
	v_div_fixup_f32 v200, v164, v163, v162
	v_exp_f32_e32 v6, v6
	v_and_b32_e32 v165, 0xffff0000, v159
	s_nop 1
	v_add_f32_e32 v6, 1.0, v6
	s_nop 0
	s_nop 3
	v_div_scale_f32 v10, s[10:11], v6, v6, v7
	s_nop 3
	v_rcp_f32_e32 v11, v10
	s_nop 1
	v_fma_f32 v160, -v10, v11, 1.0
	v_fmac_f32_e32 v11, v160, v11
	v_div_scale_f32 v160, vcc, v7, v6, v7
	s_nop 1
	v_mul_f32_e32 v161, v160, v11
	v_fma_f32 v163, -v10, v161, v160
	v_fmac_f32_e32 v161, v163, v11
	v_fma_f32 v10, -v10, v161, v160
	v_div_fmas_f32 v10, v10, v11, v161
	v_div_fixup_f32 v201, v10, v6, v7
	v_and_b32_e32 v161, 0xffff0000, v157
	v_lshlrev_b32_e32 v160, 16, v157
	v_lshlrev_b32_e32 v164, 16, v159
	s_nop 0
	s_movk_i32 s10, 0x2000
	v_add_co_u32_e32 v10, vcc, s10, v4
	s_movk_i32 s10, 0x5000
	s_nop 0
	v_addc_co_u32_e32 v11, vcc, 0, v5, vcc
	v_add_co_u32_e32 v4, vcc, s10, v4
	v_mul_f32_e32 v202, v186, v186
	v_mul_f32_e32 v203, v187, v187
	v_mul_f32_e32 v204, v188, v188
	v_mul_f32_e32 v205, v189, v189
	v_mul_f32_e32 v206, v190, v190
	v_mul_f32_e32 v207, v191, v191
	v_mul_f32_e32 v208, v192, v192
	v_mul_f32_e32 v209, v193, v193
	v_mul_f32_e32 v210, v194, v194
	v_mul_f32_e32 v211, v195, v195
	v_mul_f32_e32 v212, v196, v196
	v_mul_f32_e32 v213, v197, v197
	v_mul_f32_e32 v214, v198, v198
	v_mul_f32_e32 v215, v199, v199
	v_mul_f32_e32 v216, v200, v200
	v_mul_f32_e32 v217, v201, v201
	v_permlane32_swap_b32 v202, v210
	v_permlane32_swap_b32 v203, v211
	v_permlane32_swap_b32 v204, v212
	v_permlane32_swap_b32 v205, v213
	v_permlane32_swap_b32 v206, v214
	v_permlane32_swap_b32 v207, v215
	v_permlane32_swap_b32 v208, v216
	v_permlane32_swap_b32 v209, v217
	v_add_f32_e32 v202, v202, v210
	v_add_f32_e32 v203, v203, v211
	v_add_f32_e32 v204, v204, v212
	v_add_f32_e32 v205, v205, v213
	v_add_f32_e32 v206, v206, v214
	v_add_f32_e32 v207, v207, v215
	v_add_f32_e32 v208, v208, v216
	v_add_f32_e32 v209, v209, v217
	v_permlane16_swap_b32 v202, v206
	v_permlane16_swap_b32 v203, v207
	v_permlane16_swap_b32 v204, v208
	v_permlane16_swap_b32 v205, v209
	s_mov_b32 s44, 0xff00ff00
	s_mov_b32 s45, 0xff00ff00
	v_add_f32_e32 v202, v202, v206
	v_add_f32_e32 v203, v203, v207
	v_add_f32_e32 v204, v204, v208
	v_add_f32_e32 v205, v205, v209
	v_add_u32_e32 v218, 0x400, v226
	v_add_u32_e32 v219, 0x800, v226
	v_cndmask_b32_e64 v222, v204, v202, s[44:45]
	v_cndmask_b32_e64 v223, v202, v204, s[44:45]
	v_cndmask_b32_e64 v224, v205, v203, s[44:45]
	v_cndmask_b32_e64 v225, v203, v205, s[44:45]
	v_add_u32_e32 v221, 0xc00, v226
	s_nop 0
	v_add_f32_dpp v202, v222, v223 row_ror:8 row_mask:0xf bank_mask:0xf
	v_add_f32_dpp v203, v224, v225 row_ror:8 row_mask:0xf bank_mask:0xf
	s_nop 0
	v_add_f32_dpp v202, v202, v202 quad_perm:[1,0,3,2] row_mask:0xf bank_mask:0xf
	v_add_f32_dpp v203, v203, v203 quad_perm:[1,0,3,2] row_mask:0xf bank_mask:0xf
	s_nop 0
	v_add_f32_dpp v202, v202, v202 quad_perm:[2,3,0,1] row_mask:0xf bank_mask:0xf
	v_add_f32_dpp v203, v203, v203 quad_perm:[2,3,0,1] row_mask:0xf bank_mask:0xf
	s_nop 0
	v_add_f32_dpp v202, v202, v202 row_half_mirror row_mask:0xf bank_mask:0xf
	v_add_f32_dpp v203, v203, v203 row_half_mirror row_mask:0xf bank_mask:0xf
	v_add_f32_e32 v202, 0x358637bd, v202
	v_add_f32_e32 v203, 0x358637bd, v203
	v_rsq_f32_e32 v202, v202
	v_rsq_f32_e32 v203, v203
	s_nop 0
	v_mul_f32_e32 v202, 0x3e000000, v202
	v_mul_f32_e32 v203, 0x3e000000, v203
	s_nop 0
	v_readlane_b32 s44, v202, 0
	v_readlane_b32 s45, v203, 0
	v_readlane_b32 s10, v202, 8
	v_readlane_b32 s11, v203, 8
	v_mul_f32_e32 v186, s44, v186
	v_mul_f32_e32 v187, s45, v187
	v_mul_f32_e32 v188, s10, v188
	v_mul_f32_e32 v189, s11, v189
	ds_write2_b32 v226, v186, v187 offset1:68
	ds_write2_b32 v226, v188, v189 offset0:136 offset1:204
	v_readlane_b32 s44, v202, 16
	v_readlane_b32 s45, v203, 16
	v_readlane_b32 s10, v202, 24
	v_readlane_b32 s11, v203, 24
	v_mul_f32_e32 v190, s44, v190
	v_mul_f32_e32 v191, s45, v191
	v_mul_f32_e32 v192, s10, v192
	v_mul_f32_e32 v193, s11, v193
	ds_write2_b32 v218, v190, v191 offset0:16 offset1:84
	ds_write2_b32 v218, v192, v193 offset0:152 offset1:220
	v_readlane_b32 s44, v202, 32
	v_readlane_b32 s45, v203, 32
	v_readlane_b32 s10, v202, 40
	v_readlane_b32 s11, v203, 40
	v_mul_f32_e32 v194, s44, v194
	v_mul_f32_e32 v195, s45, v195
	v_mul_f32_e32 v196, s10, v196
	v_mul_f32_e32 v197, s11, v197
	ds_write2_b32 v219, v194, v195 offset0:32 offset1:100
	ds_write2_b32 v219, v196, v197 offset0:168 offset1:236
	v_readlane_b32 s44, v202, 48
	v_readlane_b32 s45, v203, 48
	v_readlane_b32 s10, v202, 56
	v_readlane_b32 s11, v203, 56
	v_mul_f32_e32 v198, s44, v198
	v_mul_f32_e32 v199, s45, v199
	v_mul_f32_e32 v200, s10, v200
	v_mul_f32_e32 v201, s11, v201
	ds_write2_b32 v221, v198, v199 offset0:48 offset1:116
	ds_write2_b32 v221, v200, v201 offset0:184 offset1:252
	global_load_dword v6, v44, s[84:85] offset:2048
	v_addc_co_u32_e32 v5, vcc, 0, v5, vcc
	global_load_dword v7, v[10:11], off
	s_nop 0
	global_load_dword v8, v[8:9], off offset:2048
	s_waitcnt vmcnt(1)
; __device__ __forceinline__ float bf2f(u16 h) { return __uint_as_float(((unsigned)h) << 16); }
; __device__ __forceinline__ float silu(float y) { return y / (1.f + __expf(-y)); }
; __device__ void ph_dnpre(const P& p, float* lds) {
;     ...
;       for (int arr = 0; arr < 3; ++arr) {
;         const int ch = arr * 512 + h * 64 + lane;
;         const float w0 = p.conv_w[ch], w1 = p.conv_w[1536 + ch], w2 = p.conv_w[3072 + ch], w3 = p.conv_w[4608 + ch];
;         float* dst = arr == 0 ? B0 : (arr == 1 ? B1 : B2);
; #pragma unroll
;         for (int i = 0; i < 16; ++i) {
;           float y = silu(w0 * bf2f(xr[arr][i]) + w1 * bf2f(xr[arr][i + 1]) + w2 * bf2f(xr[arr][i + 2]) + w3 * bf2f(xr[arr][i + 3]));
;           if (arr < 2) {
;             float ss = wave_sum(y * y);
;             y *= rsqrtf(ss + EPS) * (arr == 0 ? 0.125f : 1.f);
;           }
;           dst[(w * 16 + i) * LS + lane] = y;
;         }
;       }
	v_pk_mul_f32 v[162:163], v[6:7], v[160:161]
	global_load_dword v9, v[4:5], off
	v_add_f32_e32 v44, v162, v163
	s_waitcnt vmcnt(0)
	v_pk_mul_f32 v[166:167], v[8:9], v[164:165]
	s_nop 0
	v_add_f32_e32 v44, v44, v166
	v_add_f32_e32 v44, v44, v167
	v_mul_f32_e32 v157, 0xbfb8aa3b, v44
	v_exp_f32_e32 v157, v157
	s_nop 0
	v_add_f32_e32 v157, 1.0, v157
	v_div_scale_f32 v159, s[10:11], v157, v157, v44
	v_rcp_f32_e32 v160, v159
	s_nop 0
	v_fma_f32 v162, -v159, v160, 1.0
	v_fmac_f32_e32 v160, v162, v160
	v_div_scale_f32 v162, vcc, v44, v157, v44
	v_mul_f32_e32 v163, v162, v160
	v_fma_f32 v166, -v159, v163, v162
	v_fmac_f32_e32 v163, v166, v160
	v_fma_f32 v159, -v159, v163, v162
	v_div_fmas_f32 v159, v159, v160, v163
	v_div_fixup_f32 v186, v159, v157, v44
	v_pk_mov_b32 v[160:161], v[160:161], v[164:165] op_sel:[1,0]
	s_nop 0
	s_nop 1
	v_pk_mul_f32 v[160:161], v[6:7], v[160:161]
	s_nop 0
	v_lshlrev_b32_e32 v159, 16, v158
	v_mov_b32_e32 v158, v165
	s_nop 0
	v_pk_mul_f32 v[162:163], v[8:9], v[158:159]
	v_add_f32_e32 v157, v160, v161
	v_add_f32_e32 v157, v157, v162
	v_add_f32_e32 v157, v157, v163
	v_mul_f32_e32 v160, 0xbfb8aa3b, v157
	v_exp_f32_e32 v160, v160
	s_nop 0
	v_add_f32_e32 v160, 1.0, v160
	v_div_scale_f32 v161, s[10:11], v160, v160, v157
	v_rcp_f32_e32 v162, v161
	s_nop 0
	v_fma_f32 v163, -v161, v162, 1.0
	v_fmac_f32_e32 v162, v163, v162
	v_div_scale_f32 v163, vcc, v157, v160, v157
	v_mul_f32_e32 v166, v163, v162
	v_fma_f32 v167, -v161, v166, v163
	v_fmac_f32_e32 v166, v167, v162
	v_fma_f32 v161, -v161, v166, v163
	v_div_fmas_f32 v161, v161, v162, v166
	v_div_fixup_f32 v187, v161, v160, v157
	v_add_u32_e32 v162, 0x4400, v69
	s_nop 0
	v_mov_b32_e32 v226, v162
	v_lshlrev_b32_e32 v44, 16, v156
	v_mov_b32_e32 v156, v6
	v_mov_b32_e32 v157, v8
	v_mov_b32_e32 v160, v164
	v_mov_b32_e32 v161, v159
	v_pk_mul_f32 v[156:157], v[156:157], v[160:161]
	s_nop 0
	v_fma_f32 v156, v7, v165, v156
	v_add_f32_e32 v156, v156, v157
	v_fmac_f32_e32 v156, v9, v44
	v_mul_f32_e32 v157, 0xbfb8aa3b, v156
	v_exp_f32_e32 v157, v157
	s_nop 0
	v_add_f32_e32 v157, 1.0, v157
	v_div_scale_f32 v160, s[10:11], v157, v157, v156
	v_rcp_f32_e32 v161, v160
	s_nop 0
	v_fma_f32 v163, -v160, v161, 1.0
	v_fmac_f32_e32 v161, v163, v161
	v_div_scale_f32 v163, vcc, v156, v157, v156
	v_mul_f32_e32 v164, v163, v161
	v_fma_f32 v165, -v160, v164, v163
	v_fmac_f32_e32 v164, v165, v161
	v_fma_f32 v160, -v160, v164, v163
	v_div_fmas_f32 v160, v160, v161, v164
	v_div_fixup_f32 v188, v160, v157, v156
	v_lshlrev_b32_e32 v161, 16, v155
	s_nop 0
	v_pk_mul_f32 v[156:157], v[6:7], v[158:159]
	s_nop 0
	v_add_f32_e32 v155, v156, v157
	v_fmac_f32_e32 v155, v8, v44
	v_fmac_f32_e32 v155, v9, v161
	v_mul_f32_e32 v156, 0xbfb8aa3b, v155
	v_exp_f32_e32 v156, v156
	s_nop 0
	v_add_f32_e32 v156, 1.0, v156
	v_div_scale_f32 v157, s[10:11], v156, v156, v155
	v_rcp_f32_e32 v158, v157
	s_nop 0
	v_fma_f32 v163, -v157, v158, 1.0
	v_fmac_f32_e32 v158, v163, v158
	v_div_scale_f32 v163, vcc, v155, v156, v155
	v_mul_f32_e32 v164, v163, v158
	v_fma_f32 v165, -v157, v164, v163
	v_fmac_f32_e32 v164, v165, v158
	v_fma_f32 v157, -v157, v164, v163
	v_div_fmas_f32 v157, v157, v158, v164
	v_div_fixup_f32 v189, v157, v156, v155
	v_lshlrev_b32_e32 v156, 16, v154
	v_mul_f32_e32 v154, v7, v44
	v_fmac_f32_e32 v154, v6, v159
	v_fmac_f32_e32 v154, v8, v161
	v_fmac_f32_e32 v154, v9, v156
	s_nop 0
	v_mul_f32_e32 v155, 0xbfb8aa3b, v154
	v_exp_f32_e32 v155, v155
	s_nop 0
	v_add_f32_e32 v155, 1.0, v155
	v_div_scale_f32 v157, s[10:11], v155, v155, v154
	v_rcp_f32_e32 v158, v157
	s_nop 0
	v_fma_f32 v159, -v157, v158, 1.0
	v_fmac_f32_e32 v158, v159, v158
	v_div_scale_f32 v159, vcc, v154, v155, v154
	v_mul_f32_e32 v160, v159, v158
	v_fma_f32 v162, -v157, v160, v159
	v_fmac_f32_e32 v160, v162, v158
	v_fma_f32 v157, -v157, v160, v159
	v_div_fmas_f32 v157, v157, v158, v160
	v_div_fixup_f32 v190, v157, v155, v154
	v_lshlrev_b32_e32 v158, 16, v153
	v_mul_f32_e32 v153, v7, v161
	s_nop 1
	v_fmac_f32_e32 v153, v6, v44
	v_fmac_f32_e32 v153, v8, v156
	s_nop 0
	v_fmac_f32_e32 v153, v9, v158
	v_mul_f32_e32 v44, 0xbfb8aa3b, v153
	s_nop 0
	v_exp_f32_e32 v44, v44
	s_nop 0
	s_nop 0
	v_add_f32_e32 v44, 1.0, v44
	s_nop 4
	v_div_scale_f32 v154, s[10:11], v44, v44, v153
	v_rcp_f32_e32 v155, v154
	s_nop 0
	v_fma_f32 v159, -v154, v155, 1.0
	v_fmac_f32_e32 v155, v159, v155
	v_div_scale_f32 v159, vcc, v153, v44, v153
	v_mul_f32_e32 v160, v159, v155
	v_fma_f32 v162, -v154, v160, v159
	v_fmac_f32_e32 v160, v162, v155
	v_fma_f32 v154, -v154, v160, v159
	v_div_fmas_f32 v154, v154, v155, v160
	v_div_fixup_f32 v191, v154, v44, v153
	v_add_u32_e32 v154, 0x4800, v69
	v_lshlrev_b32_e32 v44, 16, v152
	v_mul_f32_e32 v152, v7, v156
	v_fmac_f32_e32 v152, v6, v161
	v_fmac_f32_e32 v152, v8, v158
	v_fmac_f32_e32 v152, v9, v44
	v_mul_f32_e32 v153, 0xbfb8aa3b, v152
	v_exp_f32_e32 v153, v153
	s_nop 0
	v_add_f32_e32 v153, 1.0, v153
	v_div_scale_f32 v155, s[10:11], v153, v153, v152
	v_rcp_f32_e32 v157, v155
	s_nop 0
	v_fma_f32 v159, -v155, v157, 1.0
	v_fmac_f32_e32 v157, v159, v157
	v_div_scale_f32 v159, vcc, v152, v153, v152
	v_mul_f32_e32 v160, v159, v157
	v_fma_f32 v161, -v155, v160, v159
	v_fmac_f32_e32 v160, v161, v157
	v_fma_f32 v155, -v155, v160, v159
	v_div_fmas_f32 v155, v155, v157, v160
	v_div_fixup_f32 v192, v155, v153, v152
	v_mul_f32_e32 v152, v7, v158
	v_fmac_f32_e32 v152, v6, v156
	v_fmac_f32_e32 v152, v8, v44
	v_fmac_f32_e32 v152, v9, v59
	v_mul_f32_e32 v153, 0xbfb8aa3b, v152
	v_exp_f32_e32 v153, v153
	s_nop 0
	v_add_f32_e32 v153, 1.0, v153
	v_div_scale_f32 v156, s[10:11], v153, v153, v152
	v_rcp_f32_e32 v157, v156
	s_nop 0
	v_fma_f32 v159, -v156, v157, 1.0
	v_fmac_f32_e32 v157, v159, v157
; __device__ __forceinline__ float bf2f(u16 h) { return __uint_as_float(((unsigned)h) << 16); }
; __device__ __forceinline__ float silu(float y) { return y / (1.f + __expf(-y)); }
; __device__ void ph_dnpre(const P& p, float* lds) {
;     ...
; #pragma unroll
;         for (int i = 0; i < 16; ++i) {
;           float y = silu(w0 * bf2f(xr[arr][i]) + w1 * bf2f(xr[arr][i + 1]) + w2 * bf2f(xr[arr][i + 2]) + w3 * bf2f(xr[arr][i + 3]));
;           if (arr < 2) {
;             float ss = wave_sum(y * y);
;             y *= rsqrtf(ss + EPS) * (arr == 0 ? 0.125f : 1.f);
;           }
;           dst[(w * 16 + i) * LS + lane] = y;
;         }
;       }
	v_div_scale_f32 v159, vcc, v152, v153, v152
	v_mul_f32_e32 v160, v159, v157
	v_fma_f32 v161, -v156, v160, v159
	v_fmac_f32_e32 v160, v161, v157
	v_fma_f32 v156, -v156, v160, v159
	v_div_fmas_f32 v156, v156, v157, v160
	v_div_fixup_f32 v193, v156, v153, v152
	v_mul_f32_e32 v152, v7, v44
	v_fmac_f32_e32 v152, v6, v158
	v_fmac_f32_e32 v152, v8, v59
	v_fmac_f32_e32 v152, v9, v151
	v_mul_f32_e32 v153, 0xbfb8aa3b, v152
	v_exp_f32_e32 v153, v153
	s_nop 0
	v_add_f32_e32 v153, 1.0, v153
	v_div_scale_f32 v154, s[10:11], v153, v153, v152
	v_rcp_f32_e32 v155, v154
	s_nop 0
	v_fma_f32 v156, -v154, v155, 1.0
	v_fmac_f32_e32 v155, v156, v155
	v_div_scale_f32 v156, vcc, v152, v153, v152
	v_mul_f32_e32 v157, v156, v155
	v_fma_f32 v158, -v154, v157, v156
	v_fmac_f32_e32 v157, v158, v155
	v_fma_f32 v154, -v154, v157, v156
	v_div_fmas_f32 v154, v154, v155, v157
	v_div_fixup_f32 v194, v154, v153, v152
	v_lshlrev_b32_e32 v155, 16, v39
	v_mul_f32_e32 v39, v7, v59
	s_nop 1
	v_fmac_f32_e32 v39, v6, v44
	v_fmac_f32_e32 v39, v8, v151
	s_nop 0
	v_fmac_f32_e32 v39, v9, v155
	v_mul_f32_e32 v44, 0xbfb8aa3b, v39
	s_nop 0
	v_exp_f32_e32 v44, v44
	s_nop 0
	s_nop 0
	v_add_f32_e32 v44, 1.0, v44
	s_nop 4
	v_div_scale_f32 v152, s[10:11], v44, v44, v39
	v_rcp_f32_e32 v153, v152
	s_nop 0
	v_fma_f32 v156, -v152, v153, 1.0
	v_fmac_f32_e32 v153, v156, v153
	v_div_scale_f32 v156, vcc, v39, v44, v39
	v_mul_f32_e32 v157, v156, v153
	v_fma_f32 v158, -v152, v157, v156
	v_fmac_f32_e32 v157, v158, v153
	v_fma_f32 v152, -v152, v157, v156
	v_div_fmas_f32 v152, v152, v153, v157
	v_div_fixup_f32 v195, v152, v44, v39
	v_lshlrev_b32_e32 v152, 16, v38
	v_mul_f32_e32 v38, v7, v151
	v_fmac_f32_e32 v38, v6, v59
	v_fmac_f32_e32 v38, v8, v155
	v_add_u32_e32 v44, 0x4c00, v69
	s_nop 0
	v_fmac_f32_e32 v38, v9, v152
	s_nop 0
	v_mul_f32_e32 v39, 0xbfb8aa3b, v38
	v_exp_f32_e32 v39, v39
	s_nop 0
	v_add_f32_e32 v39, 1.0, v39
	v_div_scale_f32 v59, s[10:11], v39, v39, v38
	v_rcp_f32_e32 v153, v59
	s_nop 0
	v_fma_f32 v154, -v59, v153, 1.0
	v_fmac_f32_e32 v153, v154, v153
	v_div_scale_f32 v154, vcc, v38, v39, v38
	v_mul_f32_e32 v156, v154, v153
	v_fma_f32 v157, -v59, v156, v154
	v_fmac_f32_e32 v156, v157, v153
	v_fma_f32 v59, -v59, v156, v154
	v_div_fmas_f32 v59, v59, v153, v156
	v_div_fixup_f32 v196, v59, v39, v38
	v_lshlrev_b32_e32 v153, 16, v37
	v_mul_f32_e32 v37, v7, v155
	s_nop 1
	v_fmac_f32_e32 v37, v6, v151
	v_fmac_f32_e32 v37, v8, v152
	s_nop 0
	v_fmac_f32_e32 v37, v9, v153
	s_nop 0
	s_nop 3
	v_mul_f32_e32 v38, 0xbfb8aa3b, v37
	v_exp_f32_e32 v38, v38
	s_nop 0
	v_add_f32_e32 v38, 1.0, v38
	v_div_scale_f32 v39, s[10:11], v38, v38, v37
	v_rcp_f32_e32 v151, v39
	s_nop 0
	v_fma_f32 v154, -v39, v151, 1.0
	v_fmac_f32_e32 v151, v154, v151
	v_div_scale_f32 v154, vcc, v37, v38, v37
	v_mul_f32_e32 v156, v154, v151
	v_fma_f32 v157, -v39, v156, v154
	v_fmac_f32_e32 v156, v157, v151
	v_fma_f32 v39, -v39, v156, v154
	v_div_fmas_f32 v39, v39, v151, v156
	v_div_fixup_f32 v197, v39, v38, v37
	v_lshlrev_b32_e32 v38, 16, v36
	v_mul_f32_e32 v36, v7, v152
	v_fmac_f32_e32 v36, v6, v155
	v_fmac_f32_e32 v36, v8, v153
	v_fmac_f32_e32 v36, v9, v38
	s_nop 0
	v_mul_f32_e32 v37, 0xbfb8aa3b, v36
	v_exp_f32_e32 v37, v37
	s_nop 0
	v_add_f32_e32 v37, 1.0, v37
	v_div_scale_f32 v39, s[10:11], v37, v37, v36
	v_rcp_f32_e32 v44, v39
	s_nop 0
	v_fma_f32 v59, -v39, v44, 1.0
	v_fmac_f32_e32 v44, v59, v44
	v_div_scale_f32 v59, vcc, v36, v37, v36
	v_mul_f32_e32 v151, v59, v44
	v_fma_f32 v154, -v39, v151, v59
	v_fmac_f32_e32 v151, v154, v44
	v_fma_f32 v39, -v39, v151, v59
	v_div_fmas_f32 v39, v39, v44, v151
	v_div_fixup_f32 v198, v39, v37, v36
	v_lshlrev_b32_e32 v44, 16, v35
	v_mul_f32_e32 v35, v7, v153
	s_nop 1
	v_fmac_f32_e32 v35, v6, v152
	v_fmac_f32_e32 v35, v8, v38
	s_nop 0
	v_fmac_f32_e32 v35, v9, v44
	s_nop 0
	s_nop 3
	v_mul_f32_e32 v36, 0xbfb8aa3b, v35
	v_exp_f32_e32 v36, v36
	s_nop 0
	v_add_f32_e32 v36, 1.0, v36
	v_div_scale_f32 v37, s[10:11], v36, v36, v35
	v_rcp_f32_e32 v59, v37
	s_nop 0
	v_fma_f32 v151, -v37, v59, 1.0
	v_fmac_f32_e32 v59, v151, v59
	v_div_scale_f32 v151, vcc, v35, v36, v35
	v_mul_f32_e32 v152, v151, v59
	v_fma_f32 v154, -v37, v152, v151
	v_fmac_f32_e32 v152, v154, v59
	v_fma_f32 v37, -v37, v152, v151
	v_div_fmas_f32 v37, v37, v59, v152
	v_div_fixup_f32 v199, v37, v36, v35
	v_lshlrev_b32_e32 v37, 16, v34
	v_mul_f32_e32 v34, v7, v38
	v_fmac_f32_e32 v34, v6, v153
	v_fmac_f32_e32 v34, v8, v44
	v_add_u32_e32 v36, 0x5000, v69
	s_nop 0
	v_fmac_f32_e32 v34, v9, v37
	s_nop 0
	v_mul_f32_e32 v35, 0xbfb8aa3b, v34
	v_exp_f32_e32 v35, v35
	v_mul_f32_e32 v7, v7, v44
	v_fmac_f32_e32 v7, v6, v38
	v_fmac_f32_e32 v7, v8, v37
	v_add_f32_e32 v35, 1.0, v35
	v_div_scale_f32 v39, s[10:11], v35, v35, v34
	v_rcp_f32_e32 v59, v39
	v_lshlrev_b32_e32 v6, 16, v33
	v_fmac_f32_e32 v7, v9, v6
	v_mul_f32_e32 v6, 0xbfb8aa3b, v7
	v_fma_f32 v151, -v39, v59, 1.0
	v_fmac_f32_e32 v59, v151, v59
	v_div_scale_f32 v151, vcc, v34, v35, v34
	v_mul_f32_e32 v152, v151, v59
	v_fma_f32 v153, -v39, v152, v151
	v_fmac_f32_e32 v152, v153, v59
	v_fma_f32 v39, -v39, v152, v151
	v_div_fmas_f32 v39, v39, v59, v152
	v_div_fixup_f32 v200, v39, v35, v34
	v_exp_f32_e32 v6, v6
	s_nop 0
	s_nop 1
	v_add_f32_e32 v6, 1.0, v6
	s_nop 0
	s_nop 3
	v_div_scale_f32 v8, s[10:11], v6, v6, v7
	s_nop 3
	v_rcp_f32_e32 v9, v8
	s_nop 1
	v_fma_f32 v33, -v8, v9, 1.0
	v_fmac_f32_e32 v9, v33, v9
	v_div_scale_f32 v33, vcc, v7, v6, v7
	s_nop 1
	v_mul_f32_e32 v35, v33, v9
	v_fma_f32 v37, -v8, v35, v33
	v_fmac_f32_e32 v35, v37, v9
	v_fma_f32 v8, -v8, v35, v33
	v_div_fmas_f32 v8, v8, v9, v35
	v_div_fixup_f32 v201, v8, v6, v7
	v_mul_f32_e32 v202, v186, v186
	v_mul_f32_e32 v203, v187, v187
; __device__ __forceinline__ float bf2f(u16 h) { return __uint_as_float(((unsigned)h) << 16); }
; __device__ __forceinline__ float silu(float y) { return y / (1.f + __expf(-y)); }
; __device__ void ph_dnpre(const P& p, float* lds) {
;     ...
; #pragma unroll
;         for (int i = 0; i < 16; ++i) {
;           float y = silu(w0 * bf2f(xr[arr][i]) + w1 * bf2f(xr[arr][i + 1]) + w2 * bf2f(xr[arr][i + 2]) + w3 * bf2f(xr[arr][i + 3]));
;           if (arr < 2) {
;             float ss = wave_sum(y * y);
;             y *= rsqrtf(ss + EPS) * (arr == 0 ? 0.125f : 1.f);
;           }
;           dst[(w * 16 + i) * LS + lane] = y;
;         }
;       }
	v_mul_f32_e32 v204, v188, v188
	v_mul_f32_e32 v205, v189, v189
	v_mul_f32_e32 v206, v190, v190
	v_mul_f32_e32 v207, v191, v191
	v_mul_f32_e32 v208, v192, v192
	v_mul_f32_e32 v209, v193, v193
	v_mul_f32_e32 v210, v194, v194
	v_mul_f32_e32 v211, v195, v195
	v_mul_f32_e32 v212, v196, v196
	v_mul_f32_e32 v213, v197, v197
	v_mul_f32_e32 v214, v198, v198
	v_mul_f32_e32 v215, v199, v199
	v_mul_f32_e32 v216, v200, v200
	v_mul_f32_e32 v217, v201, v201
	v_permlane32_swap_b32 v202, v210
	v_permlane32_swap_b32 v203, v211
	v_permlane32_swap_b32 v204, v212
	v_permlane32_swap_b32 v205, v213
	v_permlane32_swap_b32 v206, v214
	v_permlane32_swap_b32 v207, v215
	v_permlane32_swap_b32 v208, v216
	v_permlane32_swap_b32 v209, v217
	v_add_f32_e32 v202, v202, v210
	v_add_f32_e32 v203, v203, v211
	v_add_f32_e32 v204, v204, v212
	v_add_f32_e32 v205, v205, v213
	v_add_f32_e32 v206, v206, v214
	v_add_f32_e32 v207, v207, v215
	v_add_f32_e32 v208, v208, v216
	v_add_f32_e32 v209, v209, v217
	v_permlane16_swap_b32 v202, v206
	v_permlane16_swap_b32 v203, v207
	v_permlane16_swap_b32 v204, v208
	v_permlane16_swap_b32 v205, v209
	s_mov_b32 s44, 0xff00ff00
	s_mov_b32 s45, 0xff00ff00
	v_add_f32_e32 v202, v202, v206
	v_add_f32_e32 v203, v203, v207
	v_add_f32_e32 v204, v204, v208
	v_add_f32_e32 v205, v205, v209
	v_add_u32_e32 v218, 0x400, v226
	v_add_u32_e32 v219, 0x800, v226
	v_cndmask_b32_e64 v222, v204, v202, s[44:45]
	v_cndmask_b32_e64 v223, v202, v204, s[44:45]
	v_cndmask_b32_e64 v224, v205, v203, s[44:45]
	v_cndmask_b32_e64 v225, v203, v205, s[44:45]
	v_add_u32_e32 v221, 0xc00, v226
	s_nop 0
	v_add_f32_dpp v202, v222, v223 row_ror:8 row_mask:0xf bank_mask:0xf
	v_add_f32_dpp v203, v224, v225 row_ror:8 row_mask:0xf bank_mask:0xf
	s_nop 0
	v_add_f32_dpp v202, v202, v202 quad_perm:[1,0,3,2] row_mask:0xf bank_mask:0xf
	v_add_f32_dpp v203, v203, v203 quad_perm:[1,0,3,2] row_mask:0xf bank_mask:0xf
	s_nop 0
	v_add_f32_dpp v202, v202, v202 quad_perm:[2,3,0,1] row_mask:0xf bank_mask:0xf
	v_add_f32_dpp v203, v203, v203 quad_perm:[2,3,0,1] row_mask:0xf bank_mask:0xf
	s_nop 0
	v_add_f32_dpp v202, v202, v202 row_half_mirror row_mask:0xf bank_mask:0xf
	v_add_f32_dpp v203, v203, v203 row_half_mirror row_mask:0xf bank_mask:0xf
	v_add_f32_e32 v202, 0x358637bd, v202
	v_add_f32_e32 v203, 0x358637bd, v203
	v_rsq_f32_e32 v202, v202
	v_rsq_f32_e32 v203, v203
	s_nop 0
	v_readlane_b32 s44, v202, 0
	v_readlane_b32 s45, v203, 0
	v_readlane_b32 s10, v202, 8
	v_readlane_b32 s11, v203, 8
	v_mul_f32_e32 v186, s44, v186
	v_mul_f32_e32 v187, s45, v187
	v_mul_f32_e32 v188, s10, v188
	v_mul_f32_e32 v189, s11, v189
	ds_write2_b32 v226, v186, v187 offset1:68
	ds_write2_b32 v226, v188, v189 offset0:136 offset1:204
	v_readlane_b32 s44, v202, 16
	v_readlane_b32 s45, v203, 16
	v_readlane_b32 s10, v202, 24
	v_readlane_b32 s11, v203, 24
	v_mul_f32_e32 v190, s44, v190
	v_mul_f32_e32 v191, s45, v191
	v_mul_f32_e32 v192, s10, v192
	v_mul_f32_e32 v193, s11, v193
	ds_write2_b32 v218, v190, v191 offset0:16 offset1:84
	ds_write2_b32 v218, v192, v193 offset0:152 offset1:220
	v_readlane_b32 s44, v202, 32
	v_readlane_b32 s45, v203, 32
	v_readlane_b32 s10, v202, 40
	v_readlane_b32 s11, v203, 40
	v_mul_f32_e32 v194, s44, v194
	v_mul_f32_e32 v195, s45, v195
	v_mul_f32_e32 v196, s10, v196
	v_mul_f32_e32 v197, s11, v197
	ds_write2_b32 v219, v194, v195 offset0:32 offset1:100
	ds_write2_b32 v219, v196, v197 offset0:168 offset1:236
	v_readlane_b32 s44, v202, 48
	v_readlane_b32 s45, v203, 48
	v_readlane_b32 s10, v202, 56
	v_readlane_b32 s11, v203, 56
	v_mul_f32_e32 v198, s44, v198
	v_mul_f32_e32 v199, s45, v199
	v_mul_f32_e32 v200, s10, v200
	v_mul_f32_e32 v201, s11, v201
	ds_write2_b32 v221, v198, v199 offset0:48 offset1:116
	ds_write2_b32 v221, v200, v201 offset0:184 offset1:252
	global_load_dword v0, v[0:1], off
	s_nop 0
	global_load_dword v6, v[10:11], off offset:2048
	global_load_dword v1, v[2:3], off
	s_nop 0
	global_load_dword v2, v[4:5], off offset:2048
	v_lshlrev_b32_e32 v7, 16, v29
	v_lshlrev_b32_e32 v5, 16, v25
	v_lshlrev_b32_e32 v3, 16, v31
	v_lshlrev_b32_e32 v4, 16, v32
	s_waitcnt vmcnt(2)
	v_mul_f32_e32 v8, v6, v7
	v_fmac_f32_e32 v8, v0, v5
	s_waitcnt vmcnt(1)
	v_fmac_f32_e32 v8, v1, v3
	s_waitcnt vmcnt(0)
	v_fmac_f32_e32 v8, v2, v4
	v_mul_f32_e32 v5, 0xbfb8aa3b, v8
	v_exp_f32_e32 v5, v5
	s_nop 0
	v_add_f32_e32 v5, 1.0, v5
	v_div_scale_f32 v9, s[10:11], v5, v5, v8
	v_rcp_f32_e32 v10, v9
	s_nop 0
	v_fma_f32 v11, -v9, v10, 1.0
	v_fmac_f32_e32 v10, v11, v10
	v_div_scale_f32 v11, vcc, v8, v5, v8
	v_mul_f32_e32 v25, v11, v10
	v_fma_f32 v29, -v9, v25, v11
	v_fmac_f32_e32 v25, v29, v10
	v_fma_f32 v9, -v9, v25, v11
	v_div_fmas_f32 v9, v9, v10, v25
	v_div_fixup_f32 v5, v9, v5, v8
	v_mul_f32_e32 v9, v6, v3
	v_fmac_f32_e32 v9, v0, v7
	v_lshlrev_b32_e32 v8, 16, v30
	v_fmac_f32_e32 v9, v1, v4
	v_fmac_f32_e32 v9, v2, v8
	v_mul_f32_e32 v7, 0xbfb8aa3b, v9
	v_exp_f32_e32 v7, v7
	s_nop 0
	v_add_f32_e32 v7, 1.0, v7
	v_div_scale_f32 v10, s[10:11], v7, v7, v9
	v_rcp_f32_e32 v11, v10
	s_nop 0
	v_fma_f32 v25, -v10, v11, 1.0
	v_fmac_f32_e32 v11, v25, v11
	v_div_scale_f32 v25, vcc, v9, v7, v9
	v_mul_f32_e32 v29, v25, v11
	v_fma_f32 v30, -v10, v29, v25
	v_fmac_f32_e32 v29, v30, v11
	v_fma_f32 v10, -v10, v29, v25
	v_div_fmas_f32 v10, v10, v11, v29
	v_div_fixup_f32 v7, v10, v7, v9
	v_add_u32_e32 v9, 0x8800, v69
	ds_write2_b32 v9, v5, v7 offset1:68
	v_mul_f32_e32 v7, v6, v4
	v_fmac_f32_e32 v7, v0, v3
	v_lshlrev_b32_e32 v5, 16, v28
	v_fmac_f32_e32 v7, v1, v8
	v_fmac_f32_e32 v7, v2, v5
	v_mul_f32_e32 v3, 0xbfb8aa3b, v7
	v_exp_f32_e32 v3, v3
	s_nop 0
	v_add_f32_e32 v3, 1.0, v3
	v_div_scale_f32 v10, s[10:11], v3, v3, v7
	v_rcp_f32_e32 v11, v10
; __device__ __forceinline__ float bf2f(u16 h) { return __uint_as_float(((unsigned)h) << 16); }
; __device__ __forceinline__ float silu(float y) { return y / (1.f + __expf(-y)); }
; __device__ void ph_dnpre(const P& p, float* lds) {
;     ...
; #pragma unroll
;         for (int i = 0; i < 16; ++i) {
;           float y = silu(w0 * bf2f(xr[arr][i]) + w1 * bf2f(xr[arr][i + 1]) + w2 * bf2f(xr[arr][i + 2]) + w3 * bf2f(xr[arr][i + 3]));
;           if (arr < 2) {
;             float ss = wave_sum(y * y);
;             y *= rsqrtf(ss + EPS) * (arr == 0 ? 0.125f : 1.f);
;           }
;           dst[(w * 16 + i) * LS + lane] = y;
;         }
	s_nop 0
	v_fma_f32 v25, -v10, v11, 1.0
	v_fmac_f32_e32 v11, v25, v11
	v_div_scale_f32 v25, vcc, v7, v3, v7
	v_mul_f32_e32 v28, v25, v11
	v_fma_f32 v29, -v10, v28, v25
	v_fmac_f32_e32 v28, v29, v11
	v_fma_f32 v10, -v10, v28, v25
	v_div_fmas_f32 v10, v10, v11, v28
	v_div_fixup_f32 v3, v10, v3, v7
	v_mul_f32_e32 v10, v6, v8
	v_fmac_f32_e32 v10, v0, v4
	v_lshlrev_b32_e32 v7, 16, v27
	v_fmac_f32_e32 v10, v1, v5
	v_fmac_f32_e32 v10, v2, v7
	v_mul_f32_e32 v4, 0xbfb8aa3b, v10
	v_exp_f32_e32 v4, v4
	s_nop 0
	v_add_f32_e32 v4, 1.0, v4
	v_div_scale_f32 v11, s[10:11], v4, v4, v10
	v_rcp_f32_e32 v25, v11
	s_nop 0
	v_fma_f32 v27, -v11, v25, 1.0
	v_fmac_f32_e32 v25, v27, v25
	v_div_scale_f32 v27, vcc, v10, v4, v10
	v_mul_f32_e32 v28, v27, v25
	v_fma_f32 v29, -v11, v28, v27
	v_fmac_f32_e32 v28, v29, v25
	v_fma_f32 v11, -v11, v28, v27
	v_div_fmas_f32 v11, v11, v25, v28
	v_div_fixup_f32 v4, v11, v4, v10
	ds_write2_b32 v9, v3, v4 offset0:136 offset1:204
	v_mul_f32_e32 v4, v6, v5
	v_fmac_f32_e32 v4, v0, v8
	v_lshlrev_b32_e32 v3, 16, v26
	v_fmac_f32_e32 v4, v1, v7
	v_fmac_f32_e32 v4, v2, v3
	v_mul_f32_e32 v8, 0xbfb8aa3b, v4
	v_exp_f32_e32 v8, v8
	s_nop 0
	v_add_f32_e32 v8, 1.0, v8
	v_div_scale_f32 v9, s[10:11], v8, v8, v4
	v_rcp_f32_e32 v10, v9
	s_nop 0
	v_fma_f32 v11, -v9, v10, 1.0
	v_fmac_f32_e32 v10, v11, v10
	v_div_scale_f32 v11, vcc, v4, v8, v4
	v_mul_f32_e32 v25, v11, v10
	v_fma_f32 v26, -v9, v25, v11
	v_fmac_f32_e32 v25, v26, v10
	v_fma_f32 v9, -v9, v25, v11
	v_div_fmas_f32 v9, v9, v10, v25
	v_div_fixup_f32 v4, v9, v8, v4
	v_mul_f32_e32 v9, v6, v7
	v_fmac_f32_e32 v9, v0, v5
	v_lshlrev_b32_e32 v8, 16, v24
	v_fmac_f32_e32 v9, v1, v3
	v_fmac_f32_e32 v9, v2, v8
	v_mul_f32_e32 v5, 0xbfb8aa3b, v9
	v_exp_f32_e32 v5, v5
	s_nop 0
	v_add_f32_e32 v5, 1.0, v5
	v_div_scale_f32 v10, s[10:11], v5, v5, v9
	v_rcp_f32_e32 v11, v10
	s_nop 0
	v_fma_f32 v24, -v10, v11, 1.0
	v_fmac_f32_e32 v11, v24, v11
	v_div_scale_f32 v24, vcc, v9, v5, v9
	v_mul_f32_e32 v25, v24, v11
	v_fma_f32 v26, -v10, v25, v24
	v_fmac_f32_e32 v25, v26, v11
	v_fma_f32 v10, -v10, v25, v24
	v_div_fmas_f32 v10, v10, v11, v25
	v_div_fixup_f32 v5, v10, v5, v9
	v_add_u32_e32 v9, 0x8c00, v69
	ds_write2_b32 v9, v4, v5 offset0:16 offset1:84
	v_mul_f32_e32 v5, v6, v3
	v_fmac_f32_e32 v5, v0, v7
	v_lshlrev_b32_e32 v4, 16, v23
	v_fmac_f32_e32 v5, v1, v8
	v_fmac_f32_e32 v5, v2, v4
	v_mul_f32_e32 v7, 0xbfb8aa3b, v5
	v_exp_f32_e32 v7, v7
	s_nop 0
	v_add_f32_e32 v7, 1.0, v7
	v_div_scale_f32 v10, s[10:11], v7, v7, v5
	v_rcp_f32_e32 v11, v10
	s_nop 0
	v_fma_f32 v23, -v10, v11, 1.0
	v_fmac_f32_e32 v11, v23, v11
	v_div_scale_f32 v23, vcc, v5, v7, v5
	v_mul_f32_e32 v24, v23, v11
	v_fma_f32 v25, -v10, v24, v23
	v_fmac_f32_e32 v24, v25, v11
	v_fma_f32 v10, -v10, v24, v23
	v_div_fmas_f32 v10, v10, v11, v24
	v_div_fixup_f32 v5, v10, v7, v5
	v_mul_f32_e32 v10, v6, v8
	v_fmac_f32_e32 v10, v0, v3
	v_lshlrev_b32_e32 v7, 16, v22
	v_fmac_f32_e32 v10, v1, v4
	v_fmac_f32_e32 v10, v2, v7
	v_mul_f32_e32 v3, 0xbfb8aa3b, v10
	v_exp_f32_e32 v3, v3
	s_nop 0
	v_add_f32_e32 v3, 1.0, v3
	v_div_scale_f32 v11, s[10:11], v3, v3, v10
	v_rcp_f32_e32 v22, v11
	s_nop 0
	v_fma_f32 v23, -v11, v22, 1.0
	v_fmac_f32_e32 v22, v23, v22
	v_div_scale_f32 v23, vcc, v10, v3, v10
	v_mul_f32_e32 v24, v23, v22
	v_fma_f32 v25, -v11, v24, v23
	v_fmac_f32_e32 v24, v25, v22
	v_fma_f32 v11, -v11, v24, v23
	v_div_fmas_f32 v11, v11, v22, v24
	v_div_fixup_f32 v3, v11, v3, v10
	ds_write2_b32 v9, v5, v3 offset0:152 offset1:220
	v_mul_f32_e32 v5, v6, v4
	v_fmac_f32_e32 v5, v0, v8
	v_lshlrev_b32_e32 v3, 16, v21
	v_fmac_f32_e32 v5, v1, v7
	v_fmac_f32_e32 v5, v2, v3
	v_mul_f32_e32 v8, 0xbfb8aa3b, v5
	v_exp_f32_e32 v8, v8
	s_nop 0
	v_add_f32_e32 v8, 1.0, v8
	v_div_scale_f32 v9, s[10:11], v8, v8, v5
	v_rcp_f32_e32 v10, v9
	s_nop 0
	v_fma_f32 v11, -v9, v10, 1.0
	v_fmac_f32_e32 v10, v11, v10
	v_div_scale_f32 v11, vcc, v5, v8, v5
	v_mul_f32_e32 v21, v11, v10
	v_fma_f32 v22, -v9, v21, v11
	v_fmac_f32_e32 v21, v22, v10
	v_fma_f32 v9, -v9, v21, v11
	v_div_fmas_f32 v9, v9, v10, v21
	v_div_fixup_f32 v5, v9, v8, v5
	v_mul_f32_e32 v9, v6, v7
	v_fmac_f32_e32 v9, v0, v4
	v_lshlrev_b32_e32 v8, 16, v20
	v_fmac_f32_e32 v9, v1, v3
	v_fmac_f32_e32 v9, v2, v8
	v_mul_f32_e32 v4, 0xbfb8aa3b, v9
	v_exp_f32_e32 v4, v4
	s_nop 0
	v_add_f32_e32 v4, 1.0, v4
	v_div_scale_f32 v10, s[10:11], v4, v4, v9
	v_rcp_f32_e32 v11, v10
	s_nop 0
	v_fma_f32 v20, -v10, v11, 1.0
	v_fmac_f32_e32 v11, v20, v11
	v_div_scale_f32 v20, vcc, v9, v4, v9
	v_mul_f32_e32 v21, v20, v11
	v_fma_f32 v22, -v10, v21, v20
	v_fmac_f32_e32 v21, v22, v11
	v_fma_f32 v10, -v10, v21, v20
	v_div_fmas_f32 v10, v10, v11, v21
	v_div_fixup_f32 v4, v10, v4, v9
	v_add_u32_e32 v9, 0x9000, v69
	ds_write2_b32 v9, v5, v4 offset0:32 offset1:100
	v_mul_f32_e32 v5, v6, v3
	v_fmac_f32_e32 v5, v0, v7
	v_lshlrev_b32_e32 v4, 16, v19
	v_fmac_f32_e32 v5, v1, v8
	v_fmac_f32_e32 v5, v2, v4
	v_mul_f32_e32 v7, 0xbfb8aa3b, v5
	v_exp_f32_e32 v7, v7
	s_nop 0
	v_add_f32_e32 v7, 1.0, v7
	v_div_scale_f32 v10, s[10:11], v7, v7, v5
	v_rcp_f32_e32 v11, v10
	s_nop 0
	v_fma_f32 v19, -v10, v11, 1.0
	v_fmac_f32_e32 v11, v19, v11
	v_div_scale_f32 v19, vcc, v5, v7, v5
	v_mul_f32_e32 v20, v19, v11
	v_fma_f32 v21, -v10, v20, v19
	v_fmac_f32_e32 v20, v21, v11
	v_fma_f32 v10, -v10, v20, v19
	v_div_fmas_f32 v10, v10, v11, v20
	v_div_fixup_f32 v5, v10, v7, v5
	v_mul_f32_e32 v10, v6, v8
	v_fmac_f32_e32 v10, v0, v3
	v_lshlrev_b32_e32 v7, 16, v18
	v_fmac_f32_e32 v10, v1, v4
	v_fmac_f32_e32 v10, v2, v7
	v_mul_f32_e32 v3, 0xbfb8aa3b, v10
	v_exp_f32_e32 v3, v3
	s_nop 0
	v_add_f32_e32 v3, 1.0, v3
	v_div_scale_f32 v11, s[10:11], v3, v3, v10
	v_rcp_f32_e32 v18, v11
	s_nop 0
	v_fma_f32 v19, -v11, v18, 1.0
; __device__ __forceinline__ float bf2f(u16 h) { return __uint_as_float(((unsigned)h) << 16); }
; __device__ __forceinline__ float silu(float y) { return y / (1.f + __expf(-y)); }
; __device__ __forceinline__ float sigmoidf(float y) { return 1.f / (1.f + __expf(-y)); }
; __device__ __forceinline__ float softplusf(float x) { return x > 20.f ? x : log1pf(__expf(x)); }
; __device__ void ph_dnpre(const P& p, float* lds) {
;     ...
;         for (int i = 0; i < 16; ++i) {
;           float y = silu(w0 * bf2f(xr[arr][i]) + w1 * bf2f(xr[arr][i + 1]) + w2 * bf2f(xr[arr][i + 2]) + w3 * bf2f(xr[arr][i + 3]));
;           if (arr < 2) {
;             float ss = wave_sum(y * y);
;             y *= rsqrtf(ss + EPS) * (arr == 0 ? 0.125f : 1.f);
;           }
;           dst[(w * 16 + i) * LS + lane] = y;
;         }
;       }
;       if (w == 0) {
;         float g = -__expf(p.a_log[h]) * softplusf(ar_raw + p.dt_bias[h]);
; #pragma unroll
;         for (int o = 1; o < 64; o <<= 1) {
;           float t = __shfl_up(g, o);
;           if (lane >= o) g += t;
;         }
;         sG[lane] = g;
;         sBeta[lane] = sigmoidf(br_raw);
	v_fmac_f32_e32 v18, v19, v18
	v_div_scale_f32 v19, vcc, v10, v3, v10
	v_mul_f32_e32 v20, v19, v18
	v_fma_f32 v21, -v11, v20, v19
	v_fmac_f32_e32 v20, v21, v18
	v_fma_f32 v11, -v11, v20, v19
	v_div_fmas_f32 v11, v11, v18, v20
	v_div_fixup_f32 v3, v11, v3, v10
	ds_write2_b32 v9, v5, v3 offset0:168 offset1:236
	v_mul_f32_e32 v5, v6, v4
	v_fmac_f32_e32 v5, v0, v8
	v_lshlrev_b32_e32 v3, 16, v17
	v_fmac_f32_e32 v5, v1, v7
	v_fmac_f32_e32 v5, v2, v3
	v_mul_f32_e32 v8, 0xbfb8aa3b, v5
	v_exp_f32_e32 v8, v8
	s_nop 0
	v_add_f32_e32 v8, 1.0, v8
	v_div_scale_f32 v9, s[10:11], v8, v8, v5
	v_rcp_f32_e32 v10, v9
	s_nop 0
	v_fma_f32 v11, -v9, v10, 1.0
	v_fmac_f32_e32 v10, v11, v10
	v_div_scale_f32 v11, vcc, v5, v8, v5
	v_mul_f32_e32 v17, v11, v10
	v_fma_f32 v18, -v9, v17, v11
	v_fmac_f32_e32 v17, v18, v10
	v_fma_f32 v9, -v9, v17, v11
	v_div_fmas_f32 v9, v9, v10, v17
	v_div_fixup_f32 v5, v9, v8, v5
	v_mul_f32_e32 v9, v6, v7
	v_fmac_f32_e32 v9, v0, v4
	v_lshlrev_b32_e32 v8, 16, v16
	v_fmac_f32_e32 v9, v1, v3
	v_fmac_f32_e32 v9, v2, v8
	v_mul_f32_e32 v4, 0xbfb8aa3b, v9
	v_exp_f32_e32 v4, v4
	s_nop 0
	v_add_f32_e32 v4, 1.0, v4
	v_div_scale_f32 v10, s[10:11], v4, v4, v9
	v_rcp_f32_e32 v11, v10
	s_nop 0
	v_fma_f32 v16, -v10, v11, 1.0
	v_fmac_f32_e32 v11, v16, v11
	v_div_scale_f32 v16, vcc, v9, v4, v9
	v_mul_f32_e32 v17, v16, v11
	v_fma_f32 v18, -v10, v17, v16
	v_fmac_f32_e32 v17, v18, v11
	v_fma_f32 v10, -v10, v17, v16
	v_div_fmas_f32 v10, v10, v11, v17
	v_div_fixup_f32 v4, v10, v4, v9
	v_add_u32_e32 v9, 0x9400, v69
	ds_write2_b32 v9, v5, v4 offset0:48 offset1:116
	v_mul_f32_e32 v4, v6, v3
	v_fmac_f32_e32 v4, v0, v7
	v_fmac_f32_e32 v4, v1, v8
	v_lshlrev_b32_e32 v5, 16, v15
	v_fmac_f32_e32 v4, v2, v5
	v_mul_f32_e32 v7, 0xbfb8aa3b, v4
	v_exp_f32_e32 v7, v7
	v_mul_f32_e32 v6, v6, v8
	v_fmac_f32_e32 v6, v0, v3
	v_fmac_f32_e32 v6, v1, v5
	v_lshlrev_b32_e32 v0, 16, v14
	v_fmac_f32_e32 v6, v2, v0
	v_add_f32_e32 v7, 1.0, v7
	v_mul_f32_e32 v0, 0xbfb8aa3b, v6
	v_div_scale_f32 v10, s[10:11], v7, v7, v4
	v_exp_f32_e32 v0, v0
	v_rcp_f32_e32 v11, v10
	v_add_f32_e32 v0, 1.0, v0
	v_fma_f32 v15, -v10, v11, 1.0
	v_div_scale_f32 v1, s[10:11], v0, v0, v6
	v_fmac_f32_e32 v11, v15, v11
	v_div_scale_f32 v15, vcc, v4, v7, v4
	v_rcp_f32_e32 v2, v1
	v_mul_f32_e32 v16, v15, v11
	v_fma_f32 v17, -v10, v16, v15
	v_fmac_f32_e32 v16, v17, v11
	v_fma_f32 v10, -v10, v16, v15
	v_fma_f32 v3, -v1, v2, 1.0
	v_div_fmas_f32 v10, v10, v11, v16
	v_fmac_f32_e32 v2, v3, v2
	v_div_scale_f32 v3, vcc, v6, v0, v6
	v_mul_f32_e32 v5, v3, v2
	v_div_fixup_f32 v4, v10, v7, v4
	v_fma_f32 v7, -v1, v5, v3
	v_fmac_f32_e32 v5, v7, v2
	v_fma_f32 v1, -v1, v5, v3
	v_div_fmas_f32 v1, v1, v2, v5
	v_div_fixup_f32 v0, v1, v0, v6
	ds_write2_b32 v9, v4, v0 offset0:184 offset1:252
	s_and_saveexec_b64 s[56:57], s[0:1]
	s_cbranch_execz .LBB0_180
	v_readlane_b32 s76, v228, 33
	v_readlane_b32 s80, v228, 37
	v_readlane_b32 s81, v228, 38
	s_lshl_b32 s3, s3, 2
	v_readlane_b32 s82, v228, 39
	v_readlane_b32 s83, v228, 40
	v_readlane_b32 s84, v228, 41
	v_readlane_b32 s85, v228, 42
	v_readlane_b32 s86, v228, 43
	v_readlane_b32 s87, v228, 44
	v_readlane_b32 s88, v228, 45
	v_readlane_b32 s89, v228, 46
	s_mov_b64 s[44:45], s[80:81]
	v_mov_b32_e32 v0, s3
	s_mov_b64 s[50:51], s[86:87]
	s_mov_b64 s[48:49], s[84:85]
	global_load_dword v1, v0, s[50:51]
	s_nop 0
	global_load_dword v0, v0, s[48:49]
	v_lshlrev_b32_e32 v2, 16, v13
	s_mov_b32 s3, 0x41a00000
	v_readlane_b32 s77, v228, 34
	v_readlane_b32 s78, v228, 35
	v_readlane_b32 s79, v228, 36
	v_readlane_b32 s90, v228, 47
	v_readlane_b32 s91, v228, 48
	s_mov_b64 s[46:47], s[82:83]
	s_mov_b64 s[52:53], s[88:89]
	s_waitcnt vmcnt(1)
	v_add_f32_e32 v1, v1, v2
	v_cmp_nlt_f32_e32 vcc, s3, v1
	s_and_saveexec_b64 s[96:97], vcc
	s_cbranch_execz .LBB0_179
; __device__ __forceinline__ float softplusf(float x) { return x > 20.f ? x : log1pf(__expf(x)); }
; __device__ void ph_dnpre(const P& p, float* lds) {
;     ...
;         float g = -__expf(p.a_log[h]) * softplusf(ar_raw + p.dt_bias[h]);
	v_mul_f32_e32 v1, 0x3fb8aa3b, v1
	v_exp_f32_e32 v1, v1
	s_mov_b32 s3, 0x3f2aaaab
	v_add_f32_e32 v4, 1.0, v1
	v_frexp_mant_f32_e32 v6, v4
	v_cvt_f64_f32_e32 v[2:3], v4
	v_frexp_exp_i32_f64_e32 v2, v[2:3]
	v_cmp_gt_f32_e32 vcc, s3, v6
	v_add_f32_e32 v5, -1.0, v4
	v_sub_f32_e32 v7, v5, v4
	v_subbrev_co_u32_e32 v10, vcc, 0, v2, vcc
	v_sub_u32_e32 v2, 0, v10
	v_sub_f32_e32 v5, v1, v5
	v_add_f32_e32 v7, 1.0, v7
	v_ldexp_f32 v3, v4, v2
	v_add_f32_e32 v5, v5, v7
	v_add_f32_e32 v4, -1.0, v3
	v_add_f32_e32 v6, 1.0, v3
	v_ldexp_f32 v2, v5, v2
	v_add_f32_e32 v5, 1.0, v4
	v_add_f32_e32 v7, -1.0, v6
	v_sub_f32_e32 v5, v3, v5
	v_sub_f32_e32 v3, v3, v7
	v_add_f32_e32 v5, v2, v5
	v_add_f32_e32 v2, v2, v3
	v_add_f32_e32 v11, v6, v2
	v_rcp_f32_e32 v14, v11
	v_sub_f32_e32 v3, v11, v6
	v_sub_f32_e32 v13, v2, v3
	v_add_f32_e32 v3, v4, v5
	v_mul_f32_e32 v16, v3, v14
	v_sub_f32_e32 v2, v3, v4
	v_mul_f32_e32 v4, v11, v16
	v_fma_f32 v6, v16, v11, -v4
	v_fmac_f32_e32 v6, v16, v13
	v_sub_f32_e32 v15, v5, v2
	v_add_f32_e32 v2, v4, v6
	v_sub_f32_e32 v5, v3, v2
	v_pk_add_f32 v[8:9], v[2:3], v[4:5] neg_lo:[0,1] neg_hi:[0,1]
	v_mov_b32_e32 v7, v2
	v_pk_add_f32 v[2:3], v[8:9], v[6:7] neg_lo:[0,1] neg_hi:[0,1]
	s_mov_b32 s3, 0x3f317218
	v_add_f32_e32 v3, v15, v3
	v_add_f32_e32 v2, v2, v3
	v_add_f32_e32 v3, v5, v2
	v_mul_f32_e32 v15, v14, v3
	v_mul_f32_e32 v4, v11, v15
	v_fma_f32 v6, v15, v11, -v4
	v_fmac_f32_e32 v6, v15, v13
	v_sub_f32_e32 v5, v5, v3
	v_add_f32_e32 v11, v2, v5
	v_add_f32_e32 v2, v4, v6
	v_sub_f32_e32 v5, v3, v2
	v_pk_add_f32 v[8:9], v[2:3], v[4:5] neg_lo:[0,1] neg_hi:[0,1]
	v_mov_b32_e32 v7, v2
	v_pk_add_f32 v[2:3], v[8:9], v[6:7] neg_lo:[0,1] neg_hi:[0,1]
	s_nop 0
	v_add_f32_e32 v3, v11, v3
	v_add_f32_e32 v2, v2, v3
	v_add_f32_e32 v3, v16, v15
	v_add_f32_e32 v2, v5, v2
	v_sub_f32_e32 v4, v3, v16
	v_mul_f32_e32 v2, v14, v2
	v_sub_f32_e32 v4, v15, v4
	v_add_f32_e32 v4, v4, v2
	v_add_f32_e32 v6, v3, v4
	v_mul_f32_e32 v7, v6, v6
	v_fmamk_f32 v2, v7, 0x3e9b6dac, v70
	v_fmaak_f32 v59, v7, v2, 0x3f2aaada
	v_cvt_f32_i32_e32 v2, v10
	v_sub_f32_e32 v3, v6, v3
	v_sub_f32_e32 v3, v4, v3
	v_ldexp_f32 v8, v3, 1
	v_mul_f32_e32 v3, v6, v7
	v_ldexp_f32 v5, v6, 1
	v_pk_mul_f32 v[6:7], v[2:3], v[58:59]
	s_nop 0
	v_fma_f32 v4, v2, s3, -v6
	v_fmac_f32_e32 v4, 0xb102e308, v2
	v_pk_add_f32 v[2:3], v[6:7], v[4:5]
	s_mov_b32 s3, 0x7f800000
	v_sub_f32_e32 v5, v3, v5
	v_sub_f32_e32 v5, v7, v5
	v_add_f32_e32 v9, v8, v5
	v_mov_b32_e32 v8, v6
	v_pk_add_f32 v[6:7], v[2:3], v[6:7] neg_lo:[0,1] neg_hi:[0,1]
	v_pk_add_f32 v[10:11], v[2:3], v[8:9]
	v_mov_b32_e32 v5, v2
	v_mov_b32_e32 v7, v11
	v_pk_add_f32 v[14:15], v[4:5], v[6:7] neg_lo:[0,1] neg_hi:[0,1]
	v_pk_add_f32 v[4:5], v[4:5], v[6:7]
	v_mov_b32_e32 v8, v9
	v_pk_add_f32 v[6:7], v[4:5], v[2:3] op_sel:[1,0] op_sel_hi:[0,1] neg_lo:[0,1] neg_hi:[0,1]
	v_pk_add_f32 v[16:17], v[10:11], v[6:7] op_sel_hi:[1,0] neg_lo:[0,1] neg_hi:[0,1]
	v_mov_b32_e32 v10, v11
	v_mov_b32_e32 v11, v5
	v_pk_mov_b32 v[6:7], v[2:3], v[6:7] op_sel:[1,0]
	v_mov_b32_e32 v9, v2
	v_pk_add_f32 v[6:7], v[10:11], v[6:7] neg_lo:[0,1] neg_hi:[0,1]
	v_mov_b32_e32 v16, v14
	v_pk_add_f32 v[2:3], v[8:9], v[6:7] neg_lo:[0,1] neg_hi:[0,1]
	v_mov_b32_e32 v15, v5
	v_pk_add_f32 v[6:7], v[16:17], v[2:3]
	v_cmp_neq_f32_e32 vcc, s3, v1
	v_pk_add_f32 v[8:9], v[6:7], v[6:7] op_sel:[0,1] op_sel_hi:[1,0]
	s_mov_b32 s3, 0x33800000
	v_pk_add_f32 v[4:5], v[4:5], v[8:9] op_sel:[1,0] op_sel_hi:[0,1]
	v_mov_b32_e32 v7, v4
	v_pk_add_f32 v[10:11], v[6:7], v[14:15] neg_lo:[0,1] neg_hi:[0,1]
	v_mov_b32_e32 v3, v8
	v_sub_f32_e32 v5, v6, v10
	v_pk_add_f32 v[2:3], v[2:3], v[10:11] neg_lo:[0,1] neg_hi:[0,1]
	v_sub_f32_e32 v5, v14, v5
	v_add_f32_e32 v2, v2, v5
	v_add_f32_e32 v2, v2, v3
	v_add_f32_e32 v2, v4, v2
	v_cndmask_b32_e32 v2, v92, v2, vcc
	v_cmp_ngt_f32_e32 vcc, -1.0, v1
	s_nop 1
	v_cndmask_b32_e32 v2, v93, v2, vcc
	v_cmp_neq_f32_e32 vcc, -1.0, v1
	s_nop 1
	v_cndmask_b32_e32 v2, v94, v2, vcc
	v_cmp_lt_f32_e64 vcc, |v1|, s3
	s_nop 1
	v_cndmask_b32_e32 v1, v2, v1, vcc
